# ssm1 items paired (32 columns share one E stream), both U blocks gathered once into LDS
# baseline (speedup 1.0000x reference)
.LBB0_293:
	s_or_b64 exec, exec, s[34:35]
	s_cmp_lg_u32 s58, 3
	s_cselect_b64 s[0:1], -1, 0
	v_writelane_b32 v251, s0, 4
	s_cmp_eq_u32 s58, 3
	s_waitcnt lgkmcnt(0)
	v_writelane_b32 v251, s1, 5
	s_cselect_b64 s[0:1], -1, 0
	v_writelane_b32 v253, s0, 38
	s_barrier
	s_nop 0
	v_writelane_b32 v253, s1, 39
	s_and_b64 s[0:1], s[0:1], exec
	s_movk_i32 s0, 0x240
	s_cselect_b32 s22, 0x200, s0
	s_add_i32 s23, s22, 0x120
	v_readlane_b32 s0, v253, 4
	s_cmp_ge_i32 s0, s23
	s_cbranch_scc1 .LBB0_384
	s_lshl_b32 s42, s58, 3
	v_readlane_b32 s43, v253, 4
	s_branch .LBB0_297

.LBB0_297:
	s_mov_b32 s100, s43
	s_cmp_ge_i32 s43, s22
	s_mov_b64 s[34:35], -1
	s_cbranch_scc0 .LBB0_305
	s_sub_i32 s3, s43, s22
	s_mul_i32 s0, s3, 0x1c72
	s_lshr_b32 s2, s0, 16
	s_mul_i32 s0, s2, 9
	s_sub_i32 s3, s3, s0
	s_lshl_b32 s3, s3, 1
	s_lshr_b32 s19, s2, 1
	s_and_b32 s2, s2, 1
	s_mov_b32 s1, 0x38e38e39
	s_movk_i32 s0, 0xff00
	s_lshl_b32 s34, s19, 5
	s_mov_b32 s35, 0
	v_and_b32_e32 v2, 15, v188
	v_bfe_u32 v24, v188, 4, 2
	v_lshrrev_b32_e32 v0, 1, v188
	v_and_b32_e32 v12, 0xffffffe0, v0
	v_bfe_u32 v0, v188, 5, 1
	v_mul_u32_u24_e32 v0, 0xa00, v0
	v_lshl_or_b32 v3, s3, 4, v2
	v_mul_hi_i32 v4, v3, s1
	v_lshrrev_b32_e32 v5, 31, v4
	v_ashrrev_i32_e32 v4, 3, v4
	v_add_u32_e32 v11, v4, v5
	v_mul_lo_u32 v4, v11, 36
	v_sub_u32_e32 v10, v3, v4
	v_cmp_lt_i32_e32 vcc, 3, v10
	v_lshlrev_b32_e32 v4, 6, v10
	v_lshlrev_b32_e32 v5, 11, v11
	v_add3_u32 v5, v5, v4, s0
	v_lshlrev_b32_e32 v3, 8, v11
	v_add3_u32 v3, v3, v4, s74
	v_cndmask_b32_e32 v3, v3, v5, vcc
	v_mad_i64_i32 v[14:15], s[26:27], v3, s59, 0
	v_and_or_b32 v14, v188, 16, v14
	v_lshl_add_u64 v[14:15], s[34:35], 0, v[14:15]
	v_lshl_add_u64 v[14:15], v[14:15], 0, v[0:1]
	v_lshl_or_b32 v13, s3, 4, v2
	v_add_u32_e32 v13, 16, v13
	v_mul_hi_i32 v4, v13, s1
	v_lshrrev_b32_e32 v5, 31, v4
	v_ashrrev_i32_e32 v4, 3, v4
	v_add_u32_e32 v35, v4, v5
	v_mul_lo_u32 v4, v35, 36
	v_sub_u32_e32 v34, v13, v4
	v_cmp_lt_i32_e32 vcc, 3, v34
	v_lshlrev_b32_e32 v4, 6, v34
	v_lshlrev_b32_e32 v5, 11, v35
	v_add3_u32 v5, v5, v4, s0
	v_lshlrev_b32_e32 v13, 8, v35
	v_add3_u32 v13, v13, v4, s74
	v_cndmask_b32_e32 v13, v13, v5, vcc
	v_mad_i64_i32 v[36:37], s[26:27], v13, s59, 0
	v_and_or_b32 v36, v188, 16, v36
	v_lshl_add_u64 v[36:37], s[34:35], 0, v[36:37]
	v_lshl_add_u64 v[36:37], v[36:37], 0, v[0:1]
	v_readlane_b32 s0, v253, 10
	s_lshl_b32 s3, s19, 1
	s_add_i32 s0, s0, s3
	s_add_i32 s0, s0, s2
	s_ashr_i32 s1, s0, 31
	s_lshl_b64 s[0:1], s[0:1], 18
	v_or_b32_e32 v2, v12, v2
	v_ashrrev_i32_e32 v3, 31, v2
	v_lshlrev_b64 v[2:3], 11, v[2:3]
	v_lshl_add_u64 v[16:17], s[0:1], 0, v[2:3]
	v_lshl_or_b32 v16, v24, 4, v16
	v_mov_b32_e32 v2, 0
	v_mov_b32_e32 v3, v2
	v_mov_b32_e32 v4, v2
	v_mov_b32_e32 v5, v2
	v_mov_b32_e32 v6, v2
	v_mov_b32_e32 v7, v2
	v_mov_b32_e32 v8, v2
	v_mov_b32_e32 v9, v2
	v_mov_b32_e32 v26, v2
	v_mov_b32_e32 v27, v2
	v_mov_b32_e32 v28, v2
	v_mov_b32_e32 v29, v2
	v_mov_b32_e32 v30, v2
	v_mov_b32_e32 v31, v2
	v_mov_b32_e32 v32, v2
	v_mov_b32_e32 v33, v2
	v_readlane_b32 s28, v252, 50
	v_readlane_b32 s29, v252, 51
.LBB0_303:
	v_lshrrev_b32_e32 v18, 6, v188
	v_lshl_add_u64 v[134:135], s[94:95], 0, v[14:15]
	v_readfirstlane_b32 s0, v18
	v_lshl_add_u64 v[20:21], s[94:95], 0, v[36:37]
	v_add_co_u32_e32 v134, vcc, 0x6c00200, v134
	s_nop 1
	v_addc_co_u32_e32 v135, vcc, 0, v135, vcc
	v_add_co_u32_e32 v20, vcc, 0x6c00200, v20
	s_nop 1
	v_addc_co_u32_e32 v21, vcc, 0, v21, vcc
	s_mul_i32 s0, s0, 0xa000
	s_mov_b32 s1, 0
	s_mov_b64 s[98:99], 0x1400
	v_lshl_add_u64 v[134:135], v[134:135], 0, s[0:1]
	v_lshl_add_u64 v[20:21], v[20:21], 0, s[0:1]
	global_load_dwordx4 v[38:41], v[134:135], off
	global_load_dwordx4 v[214:217], v[20:21], off
	v_lshl_add_u64 v[134:135], v[134:135], 0, s[98:99]
	v_lshl_add_u64 v[20:21], v[20:21], 0, s[98:99]
	global_load_dwordx4 v[42:45], v[134:135], off
	global_load_dwordx4 v[218:221], v[20:21], off
	v_lshl_add_u64 v[134:135], v[134:135], 0, s[98:99]
	v_lshl_add_u64 v[20:21], v[20:21], 0, s[98:99]
	global_load_dwordx4 v[46:49], v[134:135], off
	global_load_dwordx4 v[222:225], v[20:21], off
	v_lshl_add_u64 v[134:135], v[134:135], 0, s[98:99]
	v_lshl_add_u64 v[20:21], v[20:21], 0, s[98:99]
	global_load_dwordx4 v[50:53], v[134:135], off
	global_load_dwordx4 v[226:229], v[20:21], off
	v_lshl_add_u64 v[134:135], v[134:135], 0, s[98:99]
	v_lshl_add_u64 v[20:21], v[20:21], 0, s[98:99]
	global_load_dwordx4 v[54:57], v[134:135], off
	global_load_dwordx4 v[230:233], v[20:21], off
	v_lshl_add_u64 v[134:135], v[134:135], 0, s[98:99]
	v_lshl_add_u64 v[20:21], v[20:21], 0, s[98:99]
	global_load_dwordx4 v[58:61], v[134:135], off
	global_load_dwordx4 v[234:237], v[20:21], off
	v_lshl_add_u64 v[134:135], v[134:135], 0, s[98:99]
	v_lshl_add_u64 v[20:21], v[20:21], 0, s[98:99]
	global_load_dwordx4 v[62:65], v[134:135], off
	global_load_dwordx4 v[238:241], v[20:21], off
	v_lshl_add_u64 v[134:135], v[134:135], 0, s[98:99]
	v_lshl_add_u64 v[20:21], v[20:21], 0, s[98:99]
	global_load_dwordx4 v[66:69], v[134:135], off
	global_load_dwordx4 v[242:245], v[20:21], off
	v_lshl_add_u64 v[22:23], s[94:95], 0, v[16:17]
	v_add_co_u32_e32 v18, vcc, 0x13a58000, v22
	s_nop 1
	v_addc_co_u32_e32 v19, vcc, 0, v23, vcc
	v_add_co_u32_e32 v22, vcc, 0x13a60000, v22
	s_nop 1
	v_addc_co_u32_e32 v23, vcc, 0, v23, vcc
	v_and_b32_e32 v136, 63, v188
	v_lshlrev_b32_e32 v136, 4, v136
	v_lshrrev_b32_e32 v137, 6, v188
	v_lshl_add_u32 v137, v137, 13, v136
	global_load_dwordx4 v[70:73], v[18:19], off offset:0
	global_load_dwordx4 v[102:105], v[22:23], off offset:0
	global_load_dwordx4 v[74:77], v[18:19], off offset:64
	global_load_dwordx4 v[106:109], v[22:23], off offset:64
	global_load_dwordx4 v[78:81], v[18:19], off offset:128
	global_load_dwordx4 v[110:113], v[22:23], off offset:128
	global_load_dwordx4 v[82:85], v[18:19], off offset:192
	global_load_dwordx4 v[114:117], v[22:23], off offset:192
	global_load_dwordx4 v[86:89], v[18:19], off offset:256
	global_load_dwordx4 v[118:121], v[22:23], off offset:256
	global_load_dwordx4 v[90:93], v[18:19], off offset:320
	global_load_dwordx4 v[122:125], v[22:23], off offset:320
	global_load_dwordx4 v[94:97], v[18:19], off offset:384
	global_load_dwordx4 v[126:129], v[22:23], off offset:384
	global_load_dwordx4 v[98:101], v[18:19], off offset:448
	global_load_dwordx4 v[130:133], v[22:23], off offset:448
	s_waitcnt vmcnt(31)
	ds_write_b128 v137, v[38:41] offset:0
	s_waitcnt vmcnt(30)
	ds_write_b128 v137, v[214:217] offset:32768
	s_waitcnt vmcnt(29)
	ds_write_b128 v137, v[42:45] offset:1024
	s_waitcnt vmcnt(28)
	ds_write_b128 v137, v[218:221] offset:33792
	s_waitcnt vmcnt(27)
	ds_write_b128 v137, v[46:49] offset:2048
	s_waitcnt vmcnt(26)
	ds_write_b128 v137, v[222:225] offset:34816
	s_waitcnt vmcnt(25)
	ds_write_b128 v137, v[50:53] offset:3072
	s_waitcnt vmcnt(24)
	ds_write_b128 v137, v[226:229] offset:35840
	s_waitcnt lgkmcnt(4)
	s_waitcnt vmcnt(23)
	ds_write_b128 v137, v[54:57] offset:4096
	s_waitcnt vmcnt(22)
	ds_write_b128 v137, v[230:233] offset:36864
	s_waitcnt vmcnt(21)
	ds_write_b128 v137, v[58:61] offset:5120
	s_waitcnt vmcnt(20)
	ds_write_b128 v137, v[234:237] offset:37888
	s_waitcnt vmcnt(19)
	ds_write_b128 v137, v[62:65] offset:6144
	s_waitcnt vmcnt(18)
	ds_write_b128 v137, v[238:241] offset:38912
	s_waitcnt vmcnt(17)
	ds_write_b128 v137, v[66:69] offset:7168
	s_waitcnt vmcnt(16)
	ds_write_b128 v137, v[242:245] offset:39936
	s_waitcnt lgkmcnt(0)
	s_barrier
	ds_read_b128 v[138:141], v136 offset:0
	ds_read_b128 v[142:145], v136 offset:1024
	ds_read_b128 v[146:149], v136 offset:2048
	ds_read_b128 v[150:153], v136 offset:3072
	ds_read_b128 v[154:157], v136 offset:4096
	ds_read_b128 v[158:161], v136 offset:5120
	ds_read_b128 v[162:165], v136 offset:6144
	ds_read_b128 v[166:169], v136 offset:7168
	global_load_dwordx4 v[38:41], v[18:19], off offset:512
	global_load_dwordx4 v[214:217], v[22:23], off offset:512
	global_load_dwordx4 v[42:45], v[18:19], off offset:576
	global_load_dwordx4 v[218:221], v[22:23], off offset:576
	global_load_dwordx4 v[46:49], v[18:19], off offset:640
	global_load_dwordx4 v[222:225], v[22:23], off offset:640
	global_load_dwordx4 v[50:53], v[18:19], off offset:704
	global_load_dwordx4 v[226:229], v[22:23], off offset:704
	global_load_dwordx4 v[54:57], v[18:19], off offset:768
	global_load_dwordx4 v[230:233], v[22:23], off offset:768
	global_load_dwordx4 v[58:61], v[18:19], off offset:832
	global_load_dwordx4 v[234:237], v[22:23], off offset:832
	global_load_dwordx4 v[62:65], v[18:19], off offset:896
	global_load_dwordx4 v[238:241], v[22:23], off offset:896
	global_load_dwordx4 v[66:69], v[18:19], off offset:960
	global_load_dwordx4 v[242:245], v[22:23], off offset:960
	s_waitcnt vmcnt(30) lgkmcnt(7)
	v_mfma_f32_16x16x32_bf16 v[2:5], v[70:73], v[138:141], v[2:5]
	v_mfma_f32_16x16x32_bf16 v[6:9], v[102:105], v[138:141], v[6:9]
	ds_read_b128 v[138:141], v136 offset:32768
	s_waitcnt vmcnt(28) lgkmcnt(7)
	v_mfma_f32_16x16x32_bf16 v[2:5], v[74:77], v[142:145], v[2:5]
	v_mfma_f32_16x16x32_bf16 v[6:9], v[106:109], v[142:145], v[6:9]
	ds_read_b128 v[142:145], v136 offset:33792
	s_waitcnt vmcnt(26) lgkmcnt(7)
	v_mfma_f32_16x16x32_bf16 v[2:5], v[78:81], v[146:149], v[2:5]
	v_mfma_f32_16x16x32_bf16 v[6:9], v[110:113], v[146:149], v[6:9]
	ds_read_b128 v[146:149], v136 offset:34816
	s_waitcnt vmcnt(24) lgkmcnt(7)
	v_mfma_f32_16x16x32_bf16 v[2:5], v[82:85], v[150:153], v[2:5]
	v_mfma_f32_16x16x32_bf16 v[6:9], v[114:117], v[150:153], v[6:9]
	ds_read_b128 v[150:153], v136 offset:35840
	s_waitcnt vmcnt(22) lgkmcnt(7)
	v_mfma_f32_16x16x32_bf16 v[2:5], v[86:89], v[154:157], v[2:5]
	v_mfma_f32_16x16x32_bf16 v[6:9], v[118:121], v[154:157], v[6:9]
	ds_read_b128 v[154:157], v136 offset:36864
	s_waitcnt vmcnt(20) lgkmcnt(7)
	v_mfma_f32_16x16x32_bf16 v[2:5], v[90:93], v[158:161], v[2:5]
	v_mfma_f32_16x16x32_bf16 v[6:9], v[122:125], v[158:161], v[6:9]
	ds_read_b128 v[158:161], v136 offset:37888
	s_waitcnt vmcnt(18) lgkmcnt(7)
	v_mfma_f32_16x16x32_bf16 v[2:5], v[94:97], v[162:165], v[2:5]
	v_mfma_f32_16x16x32_bf16 v[6:9], v[126:129], v[162:165], v[6:9]
	ds_read_b128 v[162:165], v136 offset:38912
	s_waitcnt vmcnt(16) lgkmcnt(7)
	v_mfma_f32_16x16x32_bf16 v[2:5], v[98:101], v[166:169], v[2:5]
	v_mfma_f32_16x16x32_bf16 v[6:9], v[130:133], v[166:169], v[6:9]
	ds_read_b128 v[166:169], v136 offset:39936
	s_waitcnt lgkmcnt(7)
	v_mfma_f32_16x16x32_bf16 v[26:29], v[70:73], v[138:141], v[26:29]
	v_mfma_f32_16x16x32_bf16 v[30:33], v[102:105], v[138:141], v[30:33]
	ds_read_b128 v[138:141], v136 offset:8192
	s_waitcnt lgkmcnt(7)
	v_mfma_f32_16x16x32_bf16 v[26:29], v[74:77], v[142:145], v[26:29]
	v_mfma_f32_16x16x32_bf16 v[30:33], v[106:109], v[142:145], v[30:33]
	ds_read_b128 v[142:145], v136 offset:9216
	s_waitcnt lgkmcnt(7)
	v_mfma_f32_16x16x32_bf16 v[26:29], v[78:81], v[146:149], v[26:29]
	v_mfma_f32_16x16x32_bf16 v[30:33], v[110:113], v[146:149], v[30:33]
	ds_read_b128 v[146:149], v136 offset:10240
	s_waitcnt lgkmcnt(7)
	v_mfma_f32_16x16x32_bf16 v[26:29], v[82:85], v[150:153], v[26:29]
	v_mfma_f32_16x16x32_bf16 v[30:33], v[114:117], v[150:153], v[30:33]
	ds_read_b128 v[150:153], v136 offset:11264
	s_waitcnt lgkmcnt(7)
	v_mfma_f32_16x16x32_bf16 v[26:29], v[86:89], v[154:157], v[26:29]
	v_mfma_f32_16x16x32_bf16 v[30:33], v[118:121], v[154:157], v[30:33]
	ds_read_b128 v[154:157], v136 offset:12288
	s_waitcnt lgkmcnt(7)
	v_mfma_f32_16x16x32_bf16 v[26:29], v[90:93], v[158:161], v[26:29]
	v_mfma_f32_16x16x32_bf16 v[30:33], v[122:125], v[158:161], v[30:33]
	ds_read_b128 v[158:161], v136 offset:13312
	s_waitcnt lgkmcnt(7)
	v_mfma_f32_16x16x32_bf16 v[26:29], v[94:97], v[162:165], v[26:29]
	v_mfma_f32_16x16x32_bf16 v[30:33], v[126:129], v[162:165], v[30:33]
	ds_read_b128 v[162:165], v136 offset:14336
	s_waitcnt lgkmcnt(7)
	v_mfma_f32_16x16x32_bf16 v[26:29], v[98:101], v[166:169], v[26:29]
	v_mfma_f32_16x16x32_bf16 v[30:33], v[130:133], v[166:169], v[30:33]
	ds_read_b128 v[166:169], v136 offset:15360
	global_load_dwordx4 v[70:73], v[18:19], off offset:1024
	global_load_dwordx4 v[102:105], v[22:23], off offset:1024
	global_load_dwordx4 v[74:77], v[18:19], off offset:1088
	global_load_dwordx4 v[106:109], v[22:23], off offset:1088
	global_load_dwordx4 v[78:81], v[18:19], off offset:1152
	global_load_dwordx4 v[110:113], v[22:23], off offset:1152
	global_load_dwordx4 v[82:85], v[18:19], off offset:1216
	global_load_dwordx4 v[114:117], v[22:23], off offset:1216
	global_load_dwordx4 v[86:89], v[18:19], off offset:1280
	global_load_dwordx4 v[118:121], v[22:23], off offset:1280
	global_load_dwordx4 v[90:93], v[18:19], off offset:1344
	global_load_dwordx4 v[122:125], v[22:23], off offset:1344
	global_load_dwordx4 v[94:97], v[18:19], off offset:1408
	global_load_dwordx4 v[126:129], v[22:23], off offset:1408
	global_load_dwordx4 v[98:101], v[18:19], off offset:1472
	global_load_dwordx4 v[130:133], v[22:23], off offset:1472
	s_waitcnt vmcnt(30) lgkmcnt(7)
	v_mfma_f32_16x16x32_bf16 v[2:5], v[38:41], v[138:141], v[2:5]
	v_mfma_f32_16x16x32_bf16 v[6:9], v[214:217], v[138:141], v[6:9]
	ds_read_b128 v[138:141], v136 offset:40960
	s_waitcnt vmcnt(28) lgkmcnt(7)
	v_mfma_f32_16x16x32_bf16 v[2:5], v[42:45], v[142:145], v[2:5]
	v_mfma_f32_16x16x32_bf16 v[6:9], v[218:221], v[142:145], v[6:9]
	ds_read_b128 v[142:145], v136 offset:41984
	s_waitcnt vmcnt(26) lgkmcnt(7)
	v_mfma_f32_16x16x32_bf16 v[2:5], v[46:49], v[146:149], v[2:5]
	v_mfma_f32_16x16x32_bf16 v[6:9], v[222:225], v[146:149], v[6:9]
	ds_read_b128 v[146:149], v136 offset:43008
	s_waitcnt vmcnt(24) lgkmcnt(7)
	v_mfma_f32_16x16x32_bf16 v[2:5], v[50:53], v[150:153], v[2:5]
	v_mfma_f32_16x16x32_bf16 v[6:9], v[226:229], v[150:153], v[6:9]
	ds_read_b128 v[150:153], v136 offset:44032
	s_waitcnt vmcnt(22) lgkmcnt(7)
	v_mfma_f32_16x16x32_bf16 v[2:5], v[54:57], v[154:157], v[2:5]
	v_mfma_f32_16x16x32_bf16 v[6:9], v[230:233], v[154:157], v[6:9]
	ds_read_b128 v[154:157], v136 offset:45056
	s_waitcnt vmcnt(20) lgkmcnt(7)
	v_mfma_f32_16x16x32_bf16 v[2:5], v[58:61], v[158:161], v[2:5]
	v_mfma_f32_16x16x32_bf16 v[6:9], v[234:237], v[158:161], v[6:9]
	ds_read_b128 v[158:161], v136 offset:46080
	s_waitcnt vmcnt(18) lgkmcnt(7)
	v_mfma_f32_16x16x32_bf16 v[2:5], v[62:65], v[162:165], v[2:5]
	v_mfma_f32_16x16x32_bf16 v[6:9], v[238:241], v[162:165], v[6:9]
	ds_read_b128 v[162:165], v136 offset:47104
	s_waitcnt vmcnt(16) lgkmcnt(7)
	v_mfma_f32_16x16x32_bf16 v[2:5], v[66:69], v[166:169], v[2:5]
	v_mfma_f32_16x16x32_bf16 v[6:9], v[242:245], v[166:169], v[6:9]
	ds_read_b128 v[166:169], v136 offset:48128
	s_waitcnt lgkmcnt(7)
	v_mfma_f32_16x16x32_bf16 v[26:29], v[38:41], v[138:141], v[26:29]
	v_mfma_f32_16x16x32_bf16 v[30:33], v[214:217], v[138:141], v[30:33]
	ds_read_b128 v[138:141], v136 offset:16384
	s_waitcnt lgkmcnt(7)
	v_mfma_f32_16x16x32_bf16 v[26:29], v[42:45], v[142:145], v[26:29]
	v_mfma_f32_16x16x32_bf16 v[30:33], v[218:221], v[142:145], v[30:33]
	ds_read_b128 v[142:145], v136 offset:17408
	s_waitcnt lgkmcnt(7)
	v_mfma_f32_16x16x32_bf16 v[26:29], v[46:49], v[146:149], v[26:29]
	v_mfma_f32_16x16x32_bf16 v[30:33], v[222:225], v[146:149], v[30:33]
	ds_read_b128 v[146:149], v136 offset:18432
	s_waitcnt lgkmcnt(7)
	v_mfma_f32_16x16x32_bf16 v[26:29], v[50:53], v[150:153], v[26:29]
	v_mfma_f32_16x16x32_bf16 v[30:33], v[226:229], v[150:153], v[30:33]
	ds_read_b128 v[150:153], v136 offset:19456
	s_waitcnt lgkmcnt(7)
	v_mfma_f32_16x16x32_bf16 v[26:29], v[54:57], v[154:157], v[26:29]
	v_mfma_f32_16x16x32_bf16 v[30:33], v[230:233], v[154:157], v[30:33]
	ds_read_b128 v[154:157], v136 offset:20480
	s_waitcnt lgkmcnt(7)
	v_mfma_f32_16x16x32_bf16 v[26:29], v[58:61], v[158:161], v[26:29]
	v_mfma_f32_16x16x32_bf16 v[30:33], v[234:237], v[158:161], v[30:33]
	ds_read_b128 v[158:161], v136 offset:21504
	s_waitcnt lgkmcnt(7)
	v_mfma_f32_16x16x32_bf16 v[26:29], v[62:65], v[162:165], v[26:29]
	v_mfma_f32_16x16x32_bf16 v[30:33], v[238:241], v[162:165], v[30:33]
	ds_read_b128 v[162:165], v136 offset:22528
	s_waitcnt lgkmcnt(7)
	v_mfma_f32_16x16x32_bf16 v[26:29], v[66:69], v[166:169], v[26:29]
	v_mfma_f32_16x16x32_bf16 v[30:33], v[242:245], v[166:169], v[30:33]
	ds_read_b128 v[166:169], v136 offset:23552
	global_load_dwordx4 v[38:41], v[18:19], off offset:1536
	global_load_dwordx4 v[214:217], v[22:23], off offset:1536
	global_load_dwordx4 v[42:45], v[18:19], off offset:1600
	global_load_dwordx4 v[218:221], v[22:23], off offset:1600
	global_load_dwordx4 v[46:49], v[18:19], off offset:1664
	global_load_dwordx4 v[222:225], v[22:23], off offset:1664
	global_load_dwordx4 v[50:53], v[18:19], off offset:1728
	global_load_dwordx4 v[226:229], v[22:23], off offset:1728
	global_load_dwordx4 v[54:57], v[18:19], off offset:1792
	global_load_dwordx4 v[230:233], v[22:23], off offset:1792
	global_load_dwordx4 v[58:61], v[18:19], off offset:1856
	global_load_dwordx4 v[234:237], v[22:23], off offset:1856
	global_load_dwordx4 v[62:65], v[18:19], off offset:1920
	global_load_dwordx4 v[238:241], v[22:23], off offset:1920
	global_load_dwordx4 v[66:69], v[18:19], off offset:1984
	global_load_dwordx4 v[242:245], v[22:23], off offset:1984
	s_waitcnt vmcnt(30) lgkmcnt(7)
	v_mfma_f32_16x16x32_bf16 v[2:5], v[70:73], v[138:141], v[2:5]
	v_mfma_f32_16x16x32_bf16 v[6:9], v[102:105], v[138:141], v[6:9]
	ds_read_b128 v[138:141], v136 offset:49152
	s_waitcnt vmcnt(28) lgkmcnt(7)
	v_mfma_f32_16x16x32_bf16 v[2:5], v[74:77], v[142:145], v[2:5]
	v_mfma_f32_16x16x32_bf16 v[6:9], v[106:109], v[142:145], v[6:9]
	ds_read_b128 v[142:145], v136 offset:50176
	s_waitcnt vmcnt(26) lgkmcnt(7)
	v_mfma_f32_16x16x32_bf16 v[2:5], v[78:81], v[146:149], v[2:5]
	v_mfma_f32_16x16x32_bf16 v[6:9], v[110:113], v[146:149], v[6:9]
	ds_read_b128 v[146:149], v136 offset:51200
	s_waitcnt vmcnt(24) lgkmcnt(7)
	v_mfma_f32_16x16x32_bf16 v[2:5], v[82:85], v[150:153], v[2:5]
	v_mfma_f32_16x16x32_bf16 v[6:9], v[114:117], v[150:153], v[6:9]
	ds_read_b128 v[150:153], v136 offset:52224
	s_waitcnt vmcnt(22) lgkmcnt(7)
	v_mfma_f32_16x16x32_bf16 v[2:5], v[86:89], v[154:157], v[2:5]
	v_mfma_f32_16x16x32_bf16 v[6:9], v[118:121], v[154:157], v[6:9]
	ds_read_b128 v[154:157], v136 offset:53248
	s_waitcnt vmcnt(20) lgkmcnt(7)
	v_mfma_f32_16x16x32_bf16 v[2:5], v[90:93], v[158:161], v[2:5]
	v_mfma_f32_16x16x32_bf16 v[6:9], v[122:125], v[158:161], v[6:9]
	ds_read_b128 v[158:161], v136 offset:54272
	s_waitcnt vmcnt(18) lgkmcnt(7)
	v_mfma_f32_16x16x32_bf16 v[2:5], v[94:97], v[162:165], v[2:5]
	v_mfma_f32_16x16x32_bf16 v[6:9], v[126:129], v[162:165], v[6:9]
	ds_read_b128 v[162:165], v136 offset:55296
	s_waitcnt vmcnt(16) lgkmcnt(7)
	v_mfma_f32_16x16x32_bf16 v[2:5], v[98:101], v[166:169], v[2:5]
	v_mfma_f32_16x16x32_bf16 v[6:9], v[130:133], v[166:169], v[6:9]
	ds_read_b128 v[166:169], v136 offset:56320
	s_waitcnt lgkmcnt(7)
	v_mfma_f32_16x16x32_bf16 v[26:29], v[70:73], v[138:141], v[26:29]
	v_mfma_f32_16x16x32_bf16 v[30:33], v[102:105], v[138:141], v[30:33]
	ds_read_b128 v[138:141], v136 offset:24576
	s_waitcnt lgkmcnt(7)
	v_mfma_f32_16x16x32_bf16 v[26:29], v[74:77], v[142:145], v[26:29]
	v_mfma_f32_16x16x32_bf16 v[30:33], v[106:109], v[142:145], v[30:33]
	ds_read_b128 v[142:145], v136 offset:25600
	s_waitcnt lgkmcnt(7)
	v_mfma_f32_16x16x32_bf16 v[26:29], v[78:81], v[146:149], v[26:29]
	v_mfma_f32_16x16x32_bf16 v[30:33], v[110:113], v[146:149], v[30:33]
	ds_read_b128 v[146:149], v136 offset:26624
	s_waitcnt lgkmcnt(7)
	v_mfma_f32_16x16x32_bf16 v[26:29], v[82:85], v[150:153], v[26:29]
	v_mfma_f32_16x16x32_bf16 v[30:33], v[114:117], v[150:153], v[30:33]
	ds_read_b128 v[150:153], v136 offset:27648
	s_waitcnt lgkmcnt(7)
	v_mfma_f32_16x16x32_bf16 v[26:29], v[86:89], v[154:157], v[26:29]
	v_mfma_f32_16x16x32_bf16 v[30:33], v[118:121], v[154:157], v[30:33]
	ds_read_b128 v[154:157], v136 offset:28672
	s_waitcnt lgkmcnt(7)
	v_mfma_f32_16x16x32_bf16 v[26:29], v[90:93], v[158:161], v[26:29]
	v_mfma_f32_16x16x32_bf16 v[30:33], v[122:125], v[158:161], v[30:33]
	ds_read_b128 v[158:161], v136 offset:29696
	s_waitcnt lgkmcnt(7)
	v_mfma_f32_16x16x32_bf16 v[26:29], v[94:97], v[162:165], v[26:29]
	v_mfma_f32_16x16x32_bf16 v[30:33], v[126:129], v[162:165], v[30:33]
	ds_read_b128 v[162:165], v136 offset:30720
	s_waitcnt lgkmcnt(7)
	v_mfma_f32_16x16x32_bf16 v[26:29], v[98:101], v[166:169], v[26:29]
	v_mfma_f32_16x16x32_bf16 v[30:33], v[130:133], v[166:169], v[30:33]
	ds_read_b128 v[166:169], v136 offset:31744
	s_waitcnt vmcnt(14) lgkmcnt(7)
	v_mfma_f32_16x16x32_bf16 v[2:5], v[38:41], v[138:141], v[2:5]
	v_mfma_f32_16x16x32_bf16 v[6:9], v[214:217], v[138:141], v[6:9]
	ds_read_b128 v[138:141], v136 offset:57344
	s_waitcnt vmcnt(12) lgkmcnt(7)
	v_mfma_f32_16x16x32_bf16 v[2:5], v[42:45], v[142:145], v[2:5]
	v_mfma_f32_16x16x32_bf16 v[6:9], v[218:221], v[142:145], v[6:9]
	ds_read_b128 v[142:145], v136 offset:58368
	s_waitcnt vmcnt(10) lgkmcnt(7)
	v_mfma_f32_16x16x32_bf16 v[2:5], v[46:49], v[146:149], v[2:5]
	v_mfma_f32_16x16x32_bf16 v[6:9], v[222:225], v[146:149], v[6:9]
	ds_read_b128 v[146:149], v136 offset:59392
	s_waitcnt vmcnt(8) lgkmcnt(7)
	v_mfma_f32_16x16x32_bf16 v[2:5], v[50:53], v[150:153], v[2:5]
	v_mfma_f32_16x16x32_bf16 v[6:9], v[226:229], v[150:153], v[6:9]
	ds_read_b128 v[150:153], v136 offset:60416
	s_waitcnt vmcnt(6) lgkmcnt(7)
	v_mfma_f32_16x16x32_bf16 v[2:5], v[54:57], v[154:157], v[2:5]
	v_mfma_f32_16x16x32_bf16 v[6:9], v[230:233], v[154:157], v[6:9]
	ds_read_b128 v[154:157], v136 offset:61440
	s_waitcnt vmcnt(4) lgkmcnt(7)
	v_mfma_f32_16x16x32_bf16 v[2:5], v[58:61], v[158:161], v[2:5]
	v_mfma_f32_16x16x32_bf16 v[6:9], v[234:237], v[158:161], v[6:9]
	ds_read_b128 v[158:161], v136 offset:62464
	s_waitcnt vmcnt(2) lgkmcnt(7)
	v_mfma_f32_16x16x32_bf16 v[2:5], v[62:65], v[162:165], v[2:5]
	v_mfma_f32_16x16x32_bf16 v[6:9], v[238:241], v[162:165], v[6:9]
	ds_read_b128 v[162:165], v136 offset:63488
	s_waitcnt vmcnt(0) lgkmcnt(7)
	v_mfma_f32_16x16x32_bf16 v[2:5], v[66:69], v[166:169], v[2:5]
	v_mfma_f32_16x16x32_bf16 v[6:9], v[242:245], v[166:169], v[6:9]
	ds_read_b128 v[166:169], v136 offset:64512
	s_waitcnt lgkmcnt(7)
	v_mfma_f32_16x16x32_bf16 v[26:29], v[38:41], v[138:141], v[26:29]
	v_mfma_f32_16x16x32_bf16 v[30:33], v[214:217], v[138:141], v[30:33]
	s_waitcnt lgkmcnt(6)
	v_mfma_f32_16x16x32_bf16 v[26:29], v[42:45], v[142:145], v[26:29]
	v_mfma_f32_16x16x32_bf16 v[30:33], v[218:221], v[142:145], v[30:33]
	s_waitcnt lgkmcnt(5)
	v_mfma_f32_16x16x32_bf16 v[26:29], v[46:49], v[146:149], v[26:29]
	v_mfma_f32_16x16x32_bf16 v[30:33], v[222:225], v[146:149], v[30:33]
	s_waitcnt lgkmcnt(4)
	v_mfma_f32_16x16x32_bf16 v[26:29], v[50:53], v[150:153], v[26:29]
	v_mfma_f32_16x16x32_bf16 v[30:33], v[226:229], v[150:153], v[30:33]
	s_waitcnt lgkmcnt(3)
	v_mfma_f32_16x16x32_bf16 v[26:29], v[54:57], v[154:157], v[26:29]
	v_mfma_f32_16x16x32_bf16 v[30:33], v[230:233], v[154:157], v[30:33]
	s_waitcnt lgkmcnt(2)
	v_mfma_f32_16x16x32_bf16 v[26:29], v[58:61], v[158:161], v[26:29]
	v_mfma_f32_16x16x32_bf16 v[30:33], v[234:237], v[158:161], v[30:33]
	s_waitcnt lgkmcnt(1)
	v_mfma_f32_16x16x32_bf16 v[26:29], v[62:65], v[162:165], v[26:29]
	v_mfma_f32_16x16x32_bf16 v[30:33], v[238:241], v[162:165], v[30:33]
	s_waitcnt lgkmcnt(0)
	v_mfma_f32_16x16x32_bf16 v[26:29], v[66:69], v[166:169], v[26:29]
	v_mfma_f32_16x16x32_bf16 v[30:33], v[242:245], v[166:169], v[30:33]
	v_readlane_b32 s26, v253, 40
	v_readlane_b32 s27, v253, 41
	v_ashrrev_i32_e32 v13, 31, v12
	v_lshlrev_b32_e32 v20, 4, v24
	v_mov_b32_e32 v21, 0
	s_nop 7
	s_nop 7
	v_lshl_add_u32 v0, v11, 5, s3
	v_or_b32_e32 v0, s2, v0
	v_ashrrev_i32_e32 v15, 31, v10
	v_mov_b32_e32 v14, v10
	v_mad_i64_i32 v[14:15], s[0:1], v0, 36, v[14:15]
	v_lshlrev_b64 v[14:15], 9, v[14:15]
	v_lshl_add_u64 v[14:15], s[26:27], 0, v[14:15]
	v_lshl_add_u64 v[14:15], v[12:13], 2, v[14:15]
	v_lshl_add_u64 v[14:15], v[14:15], 0, v[20:21]
	global_store_dwordx4 v[14:15], v[2:5], off
	global_store_dwordx4 v[14:15], v[6:9], off offset:64
	v_lshl_add_u32 v0, v35, 5, s3
	v_or_b32_e32 v0, s2, v0
	v_ashrrev_i32_e32 v37, 31, v34
	v_mov_b32_e32 v36, v34
	v_mad_i64_i32 v[36:37], s[0:1], v0, 36, v[36:37]
	v_lshlrev_b64 v[36:37], 9, v[36:37]
	v_lshl_add_u64 v[36:37], s[26:27], 0, v[36:37]
	v_lshl_add_u64 v[36:37], v[12:13], 2, v[36:37]
	v_lshl_add_u64 v[36:37], v[36:37], 0, v[20:21]
	global_store_dwordx4 v[36:37], v[26:29], off
	global_store_dwordx4 v[36:37], v[30:33], off offset:64
	s_mov_b64 s[34:35], 0
